# v7
# speedup vs baseline: 1.0327x; 1.0117x over previous
; #define ATT_QK(S0_, S1_, kf_) do { \
;     _Pragma("unroll") for (int i_ = 0; i_ < 16; ++i_) { S0_[i_] = 0.f; S1_[i_] = 0.f; } \
;     _Pragma("unroll") for (int kk_ = 0; kk_ < 4; ++kk_) { \
;       S0_ = __builtin_amdgcn_mfma_f32_32x32x16_bf16(kf_[kk_], qf[0][kk_], S0_, 0, 0, 0); \
;       S1_ = __builtin_amdgcn_mfma_f32_32x32x16_bf16(kf_[kk_], qf[1][kk_], S1_, 0, 0, 0); } } while (0)
; #define ATT_PV(vf_, P0_, P1_) do { \
;     _Pragma("unroll") for (int c_ = 0; c_ < 2; ++c_) \
;     _Pragma("unroll") for (int db_ = 0; db_ < 2; ++db_) { \
;       O[db_][0] = __builtin_amdgcn_mfma_f32_32x32x16_bf16(vf_[db_ * 2 + c_], P0_[c_], O[db_][0], 0, 0, 0); \
;       O[db_][1] = __builtin_amdgcn_mfma_f32_32x32x16_bf16(vf_[db_ * 2 + c_], P1_[c_], O[db_][1], 0, 0, 0); } } while (0)
; __device__ __forceinline__ void exp_pack(f32x16& s, float& l, bf16x8& p0, bf16x8& p1) {
; #pragma unroll
;   for (int i = 0; i < 16; ++i) s[i] = __builtin_amdgcn_exp2f(s[i]);
;   const float a0 = (s[0] + s[1]) + (s[2] + s[3]), a1 = (s[4] + s[5]) + (s[6] + s[7]);
;   const float a2 = (s[8] + s[9]) + (s[10] + s[11]), a3 = (s[12] + s[13]) + (s[14] + s[15]);
;   l += (a0 + a1) + (a2 + a3);
;   p0 = pack8(s, 0); p1 = pack8(s, 8);
; }
; __device__ __forceinline__ void attn_item_fast(const u16* __restrict__ Qg, const u16* __restrict__ Kg, const u16* __restrict__ Vtg,
;                                                u16* __restrict__ Og, const int L, char* smem, const int tid) {
;     ...
;   for (int t = 0; t < NT; ++t) {
;     const int cur = (t & 1) * 8192;
;     const char* Kb = Ks + cur; const char* Vb = Vs + cur;
;     if (t + 1 < NT) {
;       const char* kb_ = (const char*)Kg + (size_t)(t + 1) * (64 * 256 * 2);
;       const char* vb_ = (const char*)Vtg + (size_t)(t + 1) * 128;
;       glds16(koff, kb_, ldsK + (unsigned)(cur ^ 8192)); glds16(voff, vb_, ldsV + (unsigned)(cur ^ 8192));
;     }
;     ld_kf<0>(kf, Kb, r32, hi, sw);
;     ATT_PV(vf, P0, P1);
;     ld_vf<0>(vf, Vb, r32, hi, sw);
;     ATT_QK(S0, S1, kf);
;     ld_kf<1>(kf, Kb, r32, hi, sw);
;     WBAR();
;     exp_pack(S0, l0, P0[0], P0[1]); exp_pack(S1, l1, P1[0], P1[1]);
;     WBAR();
;     ATT_PV(vf, P0, P1);
;     ld_vf<1>(vf, Vb, r32, hi, sw);
;     ATT_QK(S0, S1, kf);
;     asm volatile("s_waitcnt vmcnt(0) lgkmcnt(0)" ::: "memory");
;     WBAR();
;     exp_pack(S0, l0, P0[0], P0[1]); exp_pack(S1, l1, P1[0], P1[1]);
;     WBAR();
.LBB0_93:
	s_and_b32 s3, s53, 0x2000
	s_xor_b32 s13, s3, 0x2000
	s_add_i32 s15, s13, s49
	s_add_i32 s13, s13, s48
	s_mov_b32 s52, m0
	s_mov_b32 m0, s13
	s_nop 0
	global_load_lds_dwordx4 v179, s[34:35]
	s_mov_b32 m0, s52
	v_add_u32_e32 v82, s3, v181
	s_mov_b32 s13, m0
	s_mov_b32 m0, s15
	s_nop 0
	global_load_lds_dwordx4 v180, s[38:39]
	s_mov_b32 m0, s13
	v_add_u32_e32 v188, v82, v182
	ds_read_b128 v[146:149], v188
	s_waitcnt lgkmcnt(4)
	v_mfma_f32_32x32x16_bf16 v[50:65], v[142:145], v[74:77], v[50:65]
	v_add_u32_e32 v189, v82, v183
	ds_read_b128 v[150:153], v189
	v_add_u32_e32 v186, v82, v184
	v_add_u32_e32 v187, v82, v185
	ds_read_b128 v[154:157], v186
	ds_read_b128 v[158:161], v187
	v_mfma_f32_32x32x16_bf16 v[18:33], v[142:145], v[78:81], v[18:33]
	s_waitcnt lgkmcnt(6)
	v_mfma_f32_32x32x16_bf16 v[34:49], v[138:141], v[74:77], v[34:49]
	v_mfma_f32_32x32x16_bf16 v[2:17], v[138:141], v[78:81], v[2:17]
	s_waitcnt lgkmcnt(5)
	v_mfma_f32_32x32x16_bf16 v[50:65], v[134:137], v[70:73], v[50:65]
	v_mfma_f32_32x32x16_bf16 v[18:33], v[134:137], v[66:69], v[18:33]
	s_waitcnt lgkmcnt(4)
	v_mfma_f32_32x32x16_bf16 v[34:49], v[130:133], v[70:73], v[34:49]
	v_mfma_f32_32x32x16_bf16 v[2:17], v[130:133], v[66:69], v[2:17]
	ds_read_b128 v[142:145], v188 offset:16384
	ds_read_b128 v[134:137], v189 offset:16384
	ds_read_b128 v[138:141], v188 offset:20480
	ds_read_b128 v[130:133], v189 offset:20480
	s_waitcnt lgkmcnt(7)
	v_mfma_f32_32x32x16_bf16 v[66:81], v[146:149], v[126:129], 0
	v_mfma_f32_32x32x16_bf16 v[82:97], v[146:149], v[118:121], 0
	s_waitcnt lgkmcnt(6)
	v_mfma_f32_32x32x16_bf16 v[66:81], v[150:153], v[122:125], v[66:81]
	v_mfma_f32_32x32x16_bf16 v[82:97], v[150:153], v[114:117], v[82:97]
	s_waitcnt lgkmcnt(5)
	v_mfma_f32_32x32x16_bf16 v[66:81], v[154:157], v[110:113], v[66:81]
	v_mfma_f32_32x32x16_bf16 v[82:97], v[154:157], v[106:109], v[82:97]
	s_waitcnt lgkmcnt(4)
	v_mfma_f32_32x32x16_bf16 v[66:81], v[158:161], v[98:101], v[66:81]
	v_mfma_f32_32x32x16_bf16 v[82:97], v[158:161], v[102:105], v[82:97]
	ds_read_b128 v[146:149], v188 offset:4096
	ds_read_b128 v[150:153], v189 offset:4096
	ds_read_b128 v[154:157], v186 offset:4096
	ds_read_b128 v[158:161], v187 offset:4096
	s_barrier
	s_setprio 0
	s_nop 6
	v_exp_f32_e32 v82, v82
	v_exp_f32_e32 v188, v83
	v_exp_f32_e32 v84, v84
	v_exp_f32_e32 v206, v85
	v_exp_f32_e32 v83, v66
	v_exp_f32_e32 v189, v67
	v_exp_f32_e32 v85, v68
	v_exp_f32_e32 v207, v69
	v_exp_f32_e32 v86, v86
	v_exp_f32_e32 v208, v87
	v_exp_f32_e32 v88, v88
	v_exp_f32_e32 v210, v89
	v_exp_f32_e32 v87, v70
	v_exp_f32_e32 v209, v71
	v_exp_f32_e32 v89, v72
	v_exp_f32_e32 v211, v73
	v_exp_f32_e32 v90, v90
	v_exp_f32_e32 v212, v91
	v_exp_f32_e32 v92, v92
	v_exp_f32_e32 v214, v93
	v_exp_f32_e32 v91, v74
	v_exp_f32_e32 v213, v75
	v_exp_f32_e32 v93, v76
	v_exp_f32_e32 v215, v77
	v_exp_f32_e32 v94, v94
	v_exp_f32_e32 v216, v95
	v_exp_f32_e32 v96, v96
	v_exp_f32_e32 v218, v97
	v_exp_f32_e32 v95, v78
	v_exp_f32_e32 v217, v79
	v_exp_f32_e32 v97, v80
	v_exp_f32_e32 v219, v81
	v_add_f32_e32 v74, v82, v188
	v_add_f32_e32 v75, v83, v189
	v_add_f32_e32 v76, v84, v206
	v_add_f32_e32 v77, v85, v207
	v_add_f32_e32 v78, v88, v210
	v_add_f32_e32 v79, v89, v211
	v_add_f32_e32 v74, v74, v76
	v_add_f32_e32 v75, v75, v77
	v_add_f32_e32 v76, v86, v208
	v_add_f32_e32 v77, v87, v209
	v_add_f32_e32 v80, v92, v214
	v_add_f32_e32 v81, v93, v215
	v_add_f32_e32 v76, v76, v78
	v_add_f32_e32 v77, v77, v79
	v_add_f32_e32 v78, v90, v212
	v_add_f32_e32 v79, v91, v213
	v_add_f32_e32 v220, v96, v218
	v_add_f32_e32 v221, v97, v219
	v_add_f32_e32 v78, v78, v80
	v_add_f32_e32 v79, v79, v81
	v_add_f32_e32 v80, v94, v216
	v_add_f32_e32 v81, v95, v217
	v_add_f32_e32 v74, v74, v76
	v_add_f32_e32 v75, v75, v77
	v_add_f32_e32 v80, v80, v220
	v_add_f32_e32 v81, v81, v221
	v_cvt_pk_bf16_f32 v66, v82, v188
	v_cvt_pk_bf16_f32 v67, v84, v206
	v_cvt_pk_bf16_f32 v68, v86, v208
	v_cvt_pk_bf16_f32 v69, v88, v210
	v_cvt_pk_bf16_f32 v70, v90, v212
	s_nop 0
	v_add_f32_e32 v76, v78, v80
	v_add_f32_e32 v77, v79, v81
	v_cvt_pk_bf16_f32 v71, v92, v214
	v_cvt_pk_bf16_f32 v72, v94, v216
	v_cvt_pk_bf16_f32 v73, v96, v218
	v_cvt_pk_bf16_f32 v78, v91, v213
	v_cvt_pk_bf16_f32 v79, v93, v215
	s_nop 0
	v_add_f32_e32 v220, v74, v76
	v_add_f32_e32 v221, v75, v77
	v_cvt_pk_bf16_f32 v74, v83, v189
	v_cvt_pk_bf16_f32 v75, v85, v207
	v_cvt_pk_bf16_f32 v76, v87, v209
	v_cvt_pk_bf16_f32 v77, v89, v211
	v_cvt_pk_bf16_f32 v80, v95, v217
	v_cvt_pk_bf16_f32 v81, v97, v219
	s_barrier
	s_setprio 1
	s_waitcnt lgkmcnt(7)
	v_mfma_f32_32x32x16_bf16 v[50:65], v[142:145], v[66:69], v[50:65]
	v_mfma_f32_32x32x16_bf16 v[18:33], v[142:145], v[74:77], v[18:33]
	s_waitcnt lgkmcnt(5)
	v_mfma_f32_32x32x16_bf16 v[34:49], v[138:141], v[66:69], v[34:49]
	v_mfma_f32_32x32x16_bf16 v[2:17], v[138:141], v[74:77], v[2:17]
	v_mfma_f32_32x32x16_bf16 v[50:65], v[134:137], v[70:73], v[50:65]
	v_mfma_f32_32x32x16_bf16 v[18:33], v[134:137], v[78:81], v[18:33]
	s_waitcnt lgkmcnt(4)
	v_mfma_f32_32x32x16_bf16 v[34:49], v[130:133], v[70:73], v[34:49]
	v_mfma_f32_32x32x16_bf16 v[2:17], v[130:133], v[78:81], v[2:17]
	ds_read_b128 v[142:145], v186 offset:16384
	ds_read_b128 v[138:141], v186 offset:20480
	ds_read_b128 v[134:137], v187 offset:16384
	ds_read_b128 v[130:133], v187 offset:20480
	s_waitcnt vmcnt(0) lgkmcnt(0)
	s_waitcnt lgkmcnt(7)
	v_mfma_f32_32x32x16_bf16 v[66:81], v[146:149], v[126:129], 0
	v_mfma_f32_32x32x16_bf16 v[82:97], v[146:149], v[118:121], 0
	v_add_f32_e64 v146, v172, v220
	v_add_f32_e64 v147, v173, v221
	s_waitcnt lgkmcnt(6)
	v_mfma_f32_32x32x16_bf16 v[66:81], v[150:153], v[122:125], v[66:81]
	v_mfma_f32_32x32x16_bf16 v[82:97], v[150:153], v[114:117], v[82:97]
	s_waitcnt lgkmcnt(5)
	v_mfma_f32_32x32x16_bf16 v[66:81], v[154:157], v[110:113], v[66:81]
	v_mfma_f32_32x32x16_bf16 v[82:97], v[154:157], v[106:109], v[82:97]
	s_waitcnt lgkmcnt(4)
	v_mfma_f32_32x32x16_bf16 v[66:81], v[158:161], v[98:101], v[66:81]
	v_mfma_f32_32x32x16_bf16 v[82:97], v[158:161], v[102:105], v[82:97]
	s_barrier
; #define ATT_QK(S0_, S1_, kf_) do { \
;     _Pragma("unroll") for (int i_ = 0; i_ < 16; ++i_) { S0_[i_] = 0.f; S1_[i_] = 0.f; } \
;     _Pragma("unroll") for (int kk_ = 0; kk_ < 4; ++kk_) { \
;       S0_ = __builtin_amdgcn_mfma_f32_32x32x16_bf16(kf_[kk_], qf[0][kk_], S0_, 0, 0, 0); \
;       S1_ = __builtin_amdgcn_mfma_f32_32x32x16_bf16(kf_[kk_], qf[1][kk_], S1_, 0, 0, 0); } } while (0)
; #define ATT_PV(vf_, P0_, P1_) do { \
;     _Pragma("unroll") for (int c_ = 0; c_ < 2; ++c_) \
;     _Pragma("unroll") for (int db_ = 0; db_ < 2; ++db_) { \
;       O[db_][0] = __builtin_amdgcn_mfma_f32_32x32x16_bf16(vf_[db_ * 2 + c_], P0_[c_], O[db_][0], 0, 0, 0); \
;       O[db_][1] = __builtin_amdgcn_mfma_f32_32x32x16_bf16(vf_[db_ * 2 + c_], P1_[c_], O[db_][1], 0, 0, 0); } } while (0)
; #define WBAR() do { __builtin_amdgcn_sched_barrier(0); __builtin_amdgcn_s_barrier(); __builtin_amdgcn_sched_barrier(0); } while (0)
; __device__ __forceinline__ void attn_item_fast(const u16* __restrict__ Qg, const u16* __restrict__ Kg, const u16* __restrict__ Vtg,
;                                                u16* __restrict__ Og, const int L, char* smem, const int tid) {
;     ...
;     exp_pack(S0, l0, P0[0], P0[1]); exp_pack(S1, l1, P1[0], P1[1]);
;     WBAR();
;     ATT_PV(vf, P0, P1);
;     ld_vf<1>(vf, Vb, r32, hi, sw);
;     ATT_QK(S0, S1, kf);
;     asm volatile("s_waitcnt vmcnt(0) lgkmcnt(0)" ::: "memory");
;     WBAR();
;     exp_pack(S0, l0, P0[0], P0[1]); exp_pack(S1, l1, P1[0], P1[1]);
;     WBAR();
	s_setprio 0
	s_nop 10
	v_exp_f32_e32 v82, v82
	v_exp_f32_e32 v148, v83
	v_exp_f32_e32 v84, v84
	v_exp_f32_e32 v150, v85
	v_exp_f32_e32 v83, v66
	v_exp_f32_e32 v149, v67
	v_exp_f32_e32 v85, v68
	v_exp_f32_e32 v151, v69
	v_exp_f32_e32 v86, v86
	v_exp_f32_e32 v152, v87
	v_exp_f32_e32 v88, v88
	v_exp_f32_e32 v154, v89
	v_exp_f32_e32 v87, v70
	v_exp_f32_e32 v153, v71
	v_exp_f32_e32 v89, v72
	v_exp_f32_e32 v155, v73
	v_exp_f32_e32 v90, v90
	v_exp_f32_e32 v156, v91
	v_exp_f32_e32 v92, v92
	v_exp_f32_e32 v158, v93
	v_exp_f32_e32 v91, v74
	v_exp_f32_e32 v157, v75
	v_exp_f32_e32 v93, v76
	v_exp_f32_e32 v159, v77
	v_exp_f32_e32 v94, v94
	v_exp_f32_e32 v160, v95
	v_exp_f32_e32 v96, v96
	v_exp_f32_e32 v186, v97
	v_exp_f32_e32 v95, v78
	v_exp_f32_e32 v161, v79
	v_exp_f32_e32 v97, v80
	v_exp_f32_e32 v187, v81
	v_add_f32_e32 v66, v82, v148
	v_add_f32_e32 v67, v83, v149
	v_add_f32_e32 v68, v84, v150
	v_add_f32_e32 v69, v85, v151
	v_add_f32_e32 v70, v88, v154
	v_add_f32_e32 v71, v89, v155
	v_add_f32_e32 v66, v66, v68
	v_add_f32_e32 v67, v67, v69
	v_add_f32_e32 v68, v86, v152
	v_add_f32_e32 v69, v87, v153
	v_add_f32_e32 v72, v92, v158
	v_add_f32_e32 v73, v93, v159
	v_add_f32_e32 v68, v68, v70
	v_add_f32_e32 v69, v69, v71
	v_add_f32_e32 v70, v90, v156
	v_add_f32_e32 v71, v91, v157
	v_add_f32_e32 v74, v96, v186
	v_add_f32_e32 v75, v97, v187
	v_add_f32_e32 v70, v70, v72
	v_add_f32_e32 v71, v71, v73
	v_add_f32_e32 v72, v94, v160
	v_add_f32_e32 v73, v95, v161
	v_add_f32_e32 v66, v66, v68
	v_add_f32_e32 v67, v67, v69
	v_add_f32_e32 v72, v72, v74
	v_add_f32_e32 v73, v73, v75
	v_cvt_pk_bf16_f32 v74, v82, v148
	v_cvt_pk_bf16_f32 v75, v84, v150
	v_cvt_pk_bf16_f32 v76, v86, v152
	v_cvt_pk_bf16_f32 v77, v88, v154
	v_cvt_pk_bf16_f32 v78, v83, v149
	s_nop 0
	v_add_f32_e32 v68, v70, v72
	v_add_f32_e32 v69, v71, v73
	v_cvt_pk_bf16_f32 v70, v90, v156
	v_cvt_pk_bf16_f32 v71, v92, v158
	v_cvt_pk_bf16_f32 v72, v94, v160
	v_cvt_pk_bf16_f32 v73, v96, v186
	v_cvt_pk_bf16_f32 v79, v85, v151
	s_nop 0
	v_add_f32_e32 v66, v66, v68
	v_add_f32_e32 v67, v67, v69
	v_cvt_pk_bf16_f32 v80, v87, v153
	v_cvt_pk_bf16_f32 v81, v89, v155
	v_cvt_pk_bf16_f32 v68, v95, v161
	v_cvt_pk_bf16_f32 v69, v97, v187
	s_nop 0
	v_add_f32_e32 v172, v146, v66
	v_add_f32_e32 v173, v147, v67
	v_cvt_pk_bf16_f32 v66, v91, v157
	v_cvt_pk_bf16_f32 v67, v93, v159
	s_barrier
	s_setprio 1
	s_addk_i32 s53, 0x2000
	s_add_u32 s34, s34, 0x8000
	s_addc_u32 s35, s35, 0
	s_add_u32 s38, s38, 0x80
	s_addc_u32 s39, s39, 0
	s_cmp_eq_u32 s53, 0x1fe000
	s_cbranch_scc0 .LBB0_93
	v_add_u32_e32 v205, v181, v182
	ds_read_b128 v[146:149], v205 offset:8192
	s_waitcnt lgkmcnt(4)
	v_mfma_f32_32x32x16_bf16 v[50:65], v[142:145], v[74:77], v[50:65]
	v_add_u32_e32 v222, v181, v183
	ds_read_b128 v[150:153], v222 offset:8192
	v_add_u32_e32 v234, v181, v184
	ds_read_b128 v[154:157], v234 offset:8192
	v_add_u32_e32 v235, v181, v185
	ds_read_b128 v[158:161], v235 offset:8192
	ds_read_b128 v[186:189], v205 offset:24576
	ds_read_b128 v[206:209], v222 offset:24576
	ds_read_b128 v[210:213], v205 offset:28672
	ds_read_b128 v[214:217], v222 offset:28672
	v_mfma_f32_32x32x16_bf16 v[18:33], v[142:145], v[78:81], v[18:33]
	ds_read_b128 v[218:221], v205 offset:12288
	ds_read_b128 v[222:225], v222 offset:12288
	ds_read_b128 v[226:229], v234 offset:12288
	ds_read_b128 v[230:233], v235 offset:12288
	s_waitcnt lgkmcnt(14)
	v_mfma_f32_32x32x16_bf16 v[34:49], v[138:141], v[74:77], v[34:49]
	v_mfma_f32_32x32x16_bf16 v[2:17], v[138:141], v[78:81], v[2:17]
	s_waitcnt lgkmcnt(13)
	v_mfma_f32_32x32x16_bf16 v[50:65], v[134:137], v[70:73], v[50:65]
	v_mfma_f32_32x32x16_bf16 v[18:33], v[134:137], v[66:69], v[18:33]
	s_waitcnt lgkmcnt(12)
	v_mfma_f32_32x32x16_bf16 v[34:49], v[130:133], v[70:73], v[34:49]
	v_mfma_f32_32x32x16_bf16 v[2:17], v[130:133], v[66:69], v[2:17]
	s_waitcnt lgkmcnt(11)
	v_mfma_f32_32x32x16_bf16 v[82:97], v[146:149], v[118:121], 0
	v_mfma_f32_32x32x16_bf16 v[66:81], v[146:149], v[126:129], 0
	s_waitcnt lgkmcnt(10)
	v_mfma_f32_32x32x16_bf16 v[82:97], v[150:153], v[114:117], v[82:97]
	v_mfma_f32_32x32x16_bf16 v[66:81], v[150:153], v[122:125], v[66:81]
	s_waitcnt lgkmcnt(9)
	v_mfma_f32_32x32x16_bf16 v[82:97], v[154:157], v[106:109], v[82:97]
	v_mfma_f32_32x32x16_bf16 v[66:81], v[154:157], v[110:113], v[66:81]
	s_waitcnt lgkmcnt(8)
	v_mfma_f32_32x32x16_bf16 v[82:97], v[158:161], v[102:105], v[82:97]
	v_mfma_f32_32x32x16_bf16 v[66:81], v[158:161], v[98:101], v[66:81]
	s_barrier
; #define ATT_QK(S0_, S1_, kf_) do { \
;     _Pragma("unroll") for (int i_ = 0; i_ < 16; ++i_) { S0_[i_] = 0.f; S1_[i_] = 0.f; } \
;     _Pragma("unroll") for (int kk_ = 0; kk_ < 4; ++kk_) { \
;       S0_ = __builtin_amdgcn_mfma_f32_32x32x16_bf16(kf_[kk_], qf[0][kk_], S0_, 0, 0, 0); \
;       S1_ = __builtin_amdgcn_mfma_f32_32x32x16_bf16(kf_[kk_], qf[1][kk_], S1_, 0, 0, 0); } } while (0)
; #define ATT_PV(vf_, P0_, P1_) do { \
;     _Pragma("unroll") for (int c_ = 0; c_ < 2; ++c_) \
;     _Pragma("unroll") for (int db_ = 0; db_ < 2; ++db_) { \
;       O[db_][0] = __builtin_amdgcn_mfma_f32_32x32x16_bf16(vf_[db_ * 2 + c_], P0_[c_], O[db_][0], 0, 0, 0); \
;       O[db_][1] = __builtin_amdgcn_mfma_f32_32x32x16_bf16(vf_[db_ * 2 + c_], P1_[c_], O[db_][1], 0, 0, 0); } } while (0)
; #define WBAR() do { __builtin_amdgcn_sched_barrier(0); __builtin_amdgcn_s_barrier(); __builtin_amdgcn_sched_barrier(0); } while (0)
; __device__ __forceinline__ void attn_item_fast(const u16* __restrict__ Qg, const u16* __restrict__ Kg, const u16* __restrict__ Vtg,
;                                                u16* __restrict__ Og, const int L, char* smem, const int tid) {
;     ...
;     ld_kf<0>(kf, Kb, r32, hi, sw);
;     ATT_PV(vf, P0, P1);
;     ld_vf<0>(vf, Vb, r32, hi, sw);
;     ATT_QK(S0, S1, kf);
;     ld_kf<1>(kf, Kb, r32, hi, sw);
;     WBAR();
;     exp_pack(S0, l0, P0[0], P0[1]); exp_pack(S1, l1, P1[0], P1[1]);
;     WBAR();
;     ATT_PV(vf, P0, P1);
;     ld_vf<1>(vf, Vb, r32, hi, sw);
;     ATT_QK(S0, S1, kf);
;     asm volatile("s_waitcnt vmcnt(0) lgkmcnt(0)" ::: "memory");
;     WBAR();
;     exp_pack(S0, l0, P0[0], P0[1]); exp_pack(S1, l1, P1[0], P1[1]);
;     WBAR();
;   }
;   if (half == 0) WBAR();
	s_nop 9
	v_exp_f32_e32 v138, v82
	v_exp_f32_e32 v144, v83
	v_exp_f32_e32 v132, v84
	v_exp_f32_e32 v139, v85
	v_exp_f32_e32 v133, v86
	v_exp_f32_e32 v140, v87
	v_exp_f32_e32 v141, v88
	v_exp_f32_e32 v145, v89
	v_exp_f32_e32 v134, v90
	v_exp_f32_e32 v142, v91
	v_exp_f32_e32 v130, v92
	v_exp_f32_e32 v135, v93
	v_exp_f32_e32 v131, v94
	v_exp_f32_e32 v136, v95
	v_exp_f32_e32 v137, v96
	v_exp_f32_e32 v143, v97
	v_exp_f32_e32 v146, v66
	v_exp_f32_e32 v147, v67
	v_exp_f32_e32 v148, v68
	v_exp_f32_e32 v151, v69
	v_exp_f32_e32 v149, v70
	v_exp_f32_e32 v152, v71
	v_exp_f32_e32 v153, v72
	v_exp_f32_e32 v157, v73
	v_exp_f32_e32 v150, v74
	v_exp_f32_e32 v154, v75
	v_exp_f32_e32 v155, v76
	v_exp_f32_e32 v158, v77
	v_exp_f32_e32 v156, v78
	v_exp_f32_e32 v159, v79
	v_exp_f32_e32 v160, v80
	v_exp_f32_e32 v161, v81
	v_cvt_pk_bf16_f32 v82, v138, v144
	v_cvt_pk_bf16_f32 v83, v132, v139
	v_cvt_pk_bf16_f32 v84, v133, v140
	v_cvt_pk_bf16_f32 v85, v141, v145
	v_cvt_pk_bf16_f32 v86, v134, v142
	v_cvt_pk_bf16_f32 v87, v130, v135
	v_cvt_pk_bf16_f32 v88, v131, v136
	v_cvt_pk_bf16_f32 v89, v137, v143
	v_cvt_pk_bf16_f32 v66, v146, v147
	v_cvt_pk_bf16_f32 v67, v148, v151
	v_cvt_pk_bf16_f32 v68, v149, v152
	v_cvt_pk_bf16_f32 v69, v153, v157
	v_cvt_pk_bf16_f32 v70, v150, v154
	v_cvt_pk_bf16_f32 v71, v155, v158
	v_cvt_pk_bf16_f32 v72, v156, v159
	v_cvt_pk_bf16_f32 v73, v160, v161
	s_barrier
	s_waitcnt lgkmcnt(7)
	v_mfma_f32_32x32x16_bf16 v[50:65], v[186:189], v[82:85], v[50:65]
	v_mfma_f32_32x32x16_bf16 v[18:33], v[186:189], v[66:69], v[18:33]
	s_waitcnt lgkmcnt(5)
	v_mfma_f32_32x32x16_bf16 v[34:49], v[210:213], v[82:85], v[34:49]
	v_mfma_f32_32x32x16_bf16 v[2:17], v[210:213], v[66:69], v[2:17]
	v_mfma_f32_32x32x16_bf16 v[50:65], v[206:209], v[86:89], v[50:65]
	v_mfma_f32_32x32x16_bf16 v[18:33], v[206:209], v[70:73], v[18:33]
	s_waitcnt lgkmcnt(4)
	v_mfma_f32_32x32x16_bf16 v[34:49], v[214:217], v[86:89], v[34:49]
	v_mfma_f32_32x32x16_bf16 v[2:17], v[214:217], v[70:73], v[2:17]
	s_waitcnt lgkmcnt(3)
	v_mfma_f32_32x32x16_bf16 v[82:97], v[218:221], v[118:121], 0
	v_mfma_f32_32x32x16_bf16 v[66:81], v[218:221], v[126:129], 0
	s_waitcnt lgkmcnt(2)
	v_mfma_f32_32x32x16_bf16 v[82:97], v[222:225], v[114:117], v[82:97]
	v_mfma_f32_32x32x16_bf16 v[66:81], v[222:225], v[122:125], v[66:81]
	s_waitcnt lgkmcnt(1)
	v_mfma_f32_32x32x16_bf16 v[82:97], v[226:229], v[106:109], v[82:97]
	v_mfma_f32_32x32x16_bf16 v[66:81], v[226:229], v[110:113], v[66:81]
	s_waitcnt lgkmcnt(0)
	v_mfma_f32_32x32x16_bf16 v[82:97], v[230:233], v[102:105], v[82:97]
	ds_read_b128 v[114:117], v234 offset:24576
	ds_read_b128 v[110:113], v234 offset:28672
	ds_read_b128 v[106:109], v235 offset:24576
	ds_read_b128 v[102:105], v235 offset:28672
	s_waitcnt vmcnt(0) lgkmcnt(0)
	v_mfma_f32_32x32x16_bf16 v[66:81], v[230:233], v[98:101], v[66:81]
	s_barrier
	s_nop 5
	v_exp_f32_e32 v98, v82
	v_exp_f32_e32 v99, v83
	v_exp_f32_e32 v100, v84
	v_exp_f32_e32 v119, v85
	v_exp_f32_e32 v101, v86
	v_exp_f32_e32 v120, v87
	v_exp_f32_e32 v121, v88
	v_exp_f32_e32 v122, v89
	v_exp_f32_e32 v90, v90
	v_exp_f32_e32 v91, v91
	v_exp_f32_e32 v92, v92
	v_exp_f32_e32 v118, v93
	v_exp_f32_e32 v93, v94
	v_exp_f32_e32 v94, v95
	v_exp_f32_e32 v95, v96
	v_exp_f32_e32 v96, v97
	v_exp_f32_e32 v186, v66
	v_exp_f32_e32 v187, v67
	v_exp_f32_e32 v188, v68
	v_exp_f32_e32 v189, v69
	v_exp_f32_e32 v97, v70
	v_exp_f32_e32 v124, v71
	v_exp_f32_e32 v125, v72
	v_exp_f32_e32 v128, v73
	v_exp_f32_e32 v123, v74
	v_exp_f32_e32 v126, v75
	v_exp_f32_e32 v127, v76
	v_exp_f32_e32 v129, v77
	v_exp_f32_e32 v74, v78
	v_exp_f32_e32 v75, v79
	v_exp_f32_e32 v76, v80
	v_exp_f32_e32 v77, v81
	v_cvt_pk_bf16_f32 v86, v98, v99
	v_cvt_pk_bf16_f32 v87, v100, v119
	v_cvt_pk_bf16_f32 v88, v101, v120
	v_cvt_pk_bf16_f32 v89, v121, v122
	v_cvt_pk_bf16_f32 v82, v90, v91
	v_cvt_pk_bf16_f32 v83, v92, v118
	v_cvt_pk_bf16_f32 v84, v93, v94
	v_cvt_pk_bf16_f32 v85, v95, v96
	v_cvt_pk_bf16_f32 v70, v186, v187
	v_cvt_pk_bf16_f32 v71, v188, v189
	v_cvt_pk_bf16_f32 v72, v97, v124
	v_cvt_pk_bf16_f32 v73, v125, v128
	v_cvt_pk_bf16_f32 v66, v123, v126
	v_cvt_pk_bf16_f32 v67, v127, v129
	v_cvt_pk_bf16_f32 v68, v74, v75
	v_cvt_pk_bf16_f32 v69, v76, v77
	s_barrier
	s_cmpk_lt_u32 s14, 0x100
	s_cbranch_scc0 .LBB0_89
	s_barrier
	s_branch .LBB0_89

; #define ATT_QK(S0_, S1_, kf_) do { \
;     _Pragma("unroll") for (int i_ = 0; i_ < 16; ++i_) { S0_[i_] = 0.f; S1_[i_] = 0.f; } \
;     _Pragma("unroll") for (int kk_ = 0; kk_ < 4; ++kk_) { \
;       S0_ = __builtin_amdgcn_mfma_f32_32x32x16_bf16(kf_[kk_], qf[0][kk_], S0_, 0, 0, 0); \
;       S1_ = __builtin_amdgcn_mfma_f32_32x32x16_bf16(kf_[kk_], qf[1][kk_], S1_, 0, 0, 0); } } while (0)
; #define ATT_PV(vf_, P0_, P1_) do { \
;     _Pragma("unroll") for (int c_ = 0; c_ < 2; ++c_) \
;     _Pragma("unroll") for (int db_ = 0; db_ < 2; ++db_) { \
;       O[db_][0] = __builtin_amdgcn_mfma_f32_32x32x16_bf16(vf_[db_ * 2 + c_], P0_[c_], O[db_][0], 0, 0, 0); \
;       O[db_][1] = __builtin_amdgcn_mfma_f32_32x32x16_bf16(vf_[db_ * 2 + c_], P1_[c_], O[db_][1], 0, 0, 0); } } while (0)
; __device__ __forceinline__ void exp_pack(f32x16& s, float& l, bf16x8& p0, bf16x8& p1) {
; #pragma unroll
;   for (int i = 0; i < 16; ++i) s[i] = __builtin_amdgcn_exp2f(s[i]);
;   const float a0 = (s[0] + s[1]) + (s[2] + s[3]), a1 = (s[4] + s[5]) + (s[6] + s[7]);
;   const float a2 = (s[8] + s[9]) + (s[10] + s[11]), a3 = (s[12] + s[13]) + (s[14] + s[15]);
;   l += (a0 + a1) + (a2 + a3);
;   p0 = pack8(s, 0); p1 = pack8(s, 8);
; }
; __device__ __forceinline__ void attn_item_fast(const u16* __restrict__ Qg, const u16* __restrict__ Kg, const u16* __restrict__ Vtg,
;                                                u16* __restrict__ Og, const int L, char* smem, const int tid) {
;     ...
;   for (int t = 0; t < NT; ++t) {
;     const int cur = (t & 1) * 8192;
;     const char* Kb = Ks + cur; const char* Vb = Vs + cur;
;     if (t + 1 < NT) {
;       const char* kb_ = (const char*)Kg + (size_t)(t + 1) * (64 * 256 * 2);
;       const char* vb_ = (const char*)Vtg + (size_t)(t + 1) * 128;
;       glds16(koff, kb_, ldsK + (unsigned)(cur ^ 8192)); glds16(voff, vb_, ldsV + (unsigned)(cur ^ 8192));
;     }
;     ld_kf<0>(kf, Kb, r32, hi, sw);
;     ATT_PV(vf, P0, P1);
;     ld_vf<0>(vf, Vb, r32, hi, sw);
;     ATT_QK(S0, S1, kf);
;     ld_kf<1>(kf, Kb, r32, hi, sw);
;     WBAR();
;     exp_pack(S0, l0, P0[0], P0[1]); exp_pack(S1, l1, P1[0], P1[1]);
;     WBAR();
;     ATT_PV(vf, P0, P1);
;     ld_vf<1>(vf, Vb, r32, hi, sw);
;     ATT_QK(S0, S1, kf);
;     asm volatile("s_waitcnt vmcnt(0) lgkmcnt(0)" ::: "memory");
;     WBAR();
;     exp_pack(S0, l0, P0[0], P0[1]); exp_pack(S1, l1, P1[0], P1[1]);
;     WBAR();
.LBB0_102:
	s_and_b32 s3, s53, 0x2000
	s_xor_b32 s13, s3, 0x2000
	s_add_i32 s15, s13, s49
	s_add_i32 s13, s13, s48
	s_mov_b32 s52, m0
	s_mov_b32 m0, s13
	s_nop 0
	global_load_lds_dwordx4 v168, s[10:11]
	s_mov_b32 m0, s52
	v_add_u32_e32 v82, s3, v170
	s_mov_b32 s13, m0
	s_mov_b32 m0, s15
	s_nop 0
	global_load_lds_dwordx4 v169, s[34:35]
	s_mov_b32 m0, s13
	v_add_u32_e32 v178, v82, v171
	ds_read_b128 v[146:149], v178
	s_waitcnt lgkmcnt(4)
	v_mfma_f32_32x32x16_bf16 v[50:65], v[142:145], v[74:77], v[50:65]
	v_add_u32_e32 v179, v82, v172
	ds_read_b128 v[150:153], v179
	v_add_u32_e32 v175, v82, v173
	v_add_u32_e32 v176, v82, v174
	ds_read_b128 v[154:157], v175
	ds_read_b128 v[158:161], v176
	v_mfma_f32_32x32x16_bf16 v[18:33], v[142:145], v[78:81], v[18:33]
	s_waitcnt lgkmcnt(6)
	v_mfma_f32_32x32x16_bf16 v[34:49], v[138:141], v[74:77], v[34:49]
	v_mfma_f32_32x32x16_bf16 v[2:17], v[138:141], v[78:81], v[2:17]
	s_waitcnt lgkmcnt(5)
	v_mfma_f32_32x32x16_bf16 v[50:65], v[134:137], v[70:73], v[50:65]
	v_mfma_f32_32x32x16_bf16 v[18:33], v[134:137], v[66:69], v[18:33]
	s_waitcnt lgkmcnt(4)
	v_mfma_f32_32x32x16_bf16 v[34:49], v[130:133], v[70:73], v[34:49]
	v_mfma_f32_32x32x16_bf16 v[2:17], v[130:133], v[66:69], v[2:17]
	ds_read_b128 v[142:145], v178 offset:16384
	ds_read_b128 v[134:137], v179 offset:16384
	ds_read_b128 v[138:141], v178 offset:20480
	ds_read_b128 v[130:133], v179 offset:20480
	s_waitcnt lgkmcnt(7)
	v_mfma_f32_32x32x16_bf16 v[66:81], v[146:149], v[126:129], 0
	v_mfma_f32_32x32x16_bf16 v[82:97], v[146:149], v[118:121], 0
	s_waitcnt lgkmcnt(6)
	v_mfma_f32_32x32x16_bf16 v[66:81], v[150:153], v[122:125], v[66:81]
	v_mfma_f32_32x32x16_bf16 v[82:97], v[150:153], v[114:117], v[82:97]
	s_waitcnt lgkmcnt(5)
	v_mfma_f32_32x32x16_bf16 v[66:81], v[154:157], v[110:113], v[66:81]
	v_mfma_f32_32x32x16_bf16 v[82:97], v[154:157], v[106:109], v[82:97]
	s_waitcnt lgkmcnt(4)
	v_mfma_f32_32x32x16_bf16 v[66:81], v[158:161], v[98:101], v[66:81]
	v_mfma_f32_32x32x16_bf16 v[82:97], v[158:161], v[102:105], v[82:97]
	ds_read_b128 v[146:149], v178 offset:4096
	ds_read_b128 v[150:153], v179 offset:4096
	ds_read_b128 v[154:157], v175 offset:4096
	ds_read_b128 v[158:161], v176 offset:4096
	s_barrier
	s_setprio 0
	s_nop 6
	v_exp_f32_e32 v82, v82
	v_exp_f32_e32 v178, v83
	v_exp_f32_e32 v84, v84
	v_exp_f32_e32 v180, v85
	v_exp_f32_e32 v83, v66
	v_exp_f32_e32 v179, v67
	v_exp_f32_e32 v85, v68
	v_exp_f32_e32 v181, v69
	v_exp_f32_e32 v86, v86
	v_exp_f32_e32 v182, v87
	v_exp_f32_e32 v88, v88
	v_exp_f32_e32 v184, v89
	v_exp_f32_e32 v87, v70
	v_exp_f32_e32 v183, v71
	v_exp_f32_e32 v89, v72
	v_exp_f32_e32 v185, v73
	v_exp_f32_e32 v90, v90
	v_exp_f32_e32 v186, v91
	v_exp_f32_e32 v92, v92
	v_exp_f32_e32 v188, v93
	v_exp_f32_e32 v91, v74
	v_exp_f32_e32 v187, v75
	v_exp_f32_e32 v93, v76
	v_exp_f32_e32 v189, v77
	v_exp_f32_e32 v94, v94
	v_exp_f32_e32 v206, v95
	v_exp_f32_e32 v96, v96
	v_exp_f32_e32 v208, v97
	v_exp_f32_e32 v95, v78
	v_exp_f32_e32 v207, v79
	v_exp_f32_e32 v97, v80
	v_exp_f32_e32 v209, v81
	v_add_f32_e32 v74, v82, v178
	v_add_f32_e32 v75, v83, v179
	v_add_f32_e32 v76, v84, v180
	v_add_f32_e32 v77, v85, v181
	v_add_f32_e32 v78, v88, v184
	v_add_f32_e32 v79, v89, v185
	v_add_f32_e32 v74, v74, v76
	v_add_f32_e32 v75, v75, v77
	v_add_f32_e32 v76, v86, v182
	v_add_f32_e32 v77, v87, v183
	v_add_f32_e32 v80, v92, v188
	v_add_f32_e32 v81, v93, v189
	v_add_f32_e32 v76, v76, v78
	v_add_f32_e32 v77, v77, v79
	v_add_f32_e32 v78, v90, v186
	v_add_f32_e32 v79, v91, v187
	v_add_f32_e32 v210, v96, v208
	v_add_f32_e32 v211, v97, v209
	v_add_f32_e32 v78, v78, v80
	v_add_f32_e32 v79, v79, v81
	v_add_f32_e32 v80, v94, v206
	v_add_f32_e32 v81, v95, v207
	v_add_f32_e32 v74, v74, v76
	v_add_f32_e32 v75, v75, v77
	v_add_f32_e32 v80, v80, v210
	v_add_f32_e32 v81, v81, v211
	v_cvt_pk_bf16_f32 v66, v82, v178
	v_cvt_pk_bf16_f32 v67, v84, v180
	v_cvt_pk_bf16_f32 v68, v86, v182
	v_cvt_pk_bf16_f32 v69, v88, v184
	v_cvt_pk_bf16_f32 v70, v90, v186
	s_nop 0
	v_add_f32_e32 v76, v78, v80
	v_add_f32_e32 v77, v79, v81
	v_cvt_pk_bf16_f32 v71, v92, v188
	v_cvt_pk_bf16_f32 v72, v94, v206
	v_cvt_pk_bf16_f32 v73, v96, v208
	v_cvt_pk_bf16_f32 v78, v91, v187
	v_cvt_pk_bf16_f32 v79, v93, v189
	s_nop 0
	v_add_f32_e32 v210, v74, v76
	v_add_f32_e32 v211, v75, v77
	v_cvt_pk_bf16_f32 v74, v83, v179
	v_cvt_pk_bf16_f32 v75, v85, v181
	v_cvt_pk_bf16_f32 v76, v87, v183
	v_cvt_pk_bf16_f32 v77, v89, v185
	v_cvt_pk_bf16_f32 v80, v95, v207
	v_cvt_pk_bf16_f32 v81, v97, v209
	s_barrier
	s_setprio 1
	s_waitcnt lgkmcnt(7)
	v_mfma_f32_32x32x16_bf16 v[50:65], v[142:145], v[66:69], v[50:65]
	v_mfma_f32_32x32x16_bf16 v[18:33], v[142:145], v[74:77], v[18:33]
	s_waitcnt lgkmcnt(5)
	v_mfma_f32_32x32x16_bf16 v[34:49], v[138:141], v[66:69], v[34:49]
	v_mfma_f32_32x32x16_bf16 v[2:17], v[138:141], v[74:77], v[2:17]
	v_mfma_f32_32x32x16_bf16 v[50:65], v[134:137], v[70:73], v[50:65]
	v_mfma_f32_32x32x16_bf16 v[18:33], v[134:137], v[78:81], v[18:33]
	s_waitcnt lgkmcnt(4)
	v_mfma_f32_32x32x16_bf16 v[34:49], v[130:133], v[70:73], v[34:49]
	v_mfma_f32_32x32x16_bf16 v[2:17], v[130:133], v[78:81], v[2:17]
	ds_read_b128 v[142:145], v175 offset:16384
	ds_read_b128 v[138:141], v175 offset:20480
	ds_read_b128 v[134:137], v176 offset:16384
	ds_read_b128 v[130:133], v176 offset:20480
	s_waitcnt vmcnt(0) lgkmcnt(0)
	s_waitcnt lgkmcnt(7)
	v_mfma_f32_32x32x16_bf16 v[66:81], v[146:149], v[126:129], 0
	v_mfma_f32_32x32x16_bf16 v[82:97], v[146:149], v[118:121], 0
	v_add_f32_e64 v146, v162, v210
	v_add_f32_e64 v147, v163, v211
	s_waitcnt lgkmcnt(6)
	v_mfma_f32_32x32x16_bf16 v[66:81], v[150:153], v[122:125], v[66:81]
	v_mfma_f32_32x32x16_bf16 v[82:97], v[150:153], v[114:117], v[82:97]
	s_waitcnt lgkmcnt(5)
	v_mfma_f32_32x32x16_bf16 v[66:81], v[154:157], v[110:113], v[66:81]
	v_mfma_f32_32x32x16_bf16 v[82:97], v[154:157], v[106:109], v[82:97]
	s_waitcnt lgkmcnt(4)
	v_mfma_f32_32x32x16_bf16 v[66:81], v[158:161], v[98:101], v[66:81]
	v_mfma_f32_32x32x16_bf16 v[82:97], v[158:161], v[102:105], v[82:97]
	s_barrier
; #define ATT_QK(S0_, S1_, kf_) do { \
;     _Pragma("unroll") for (int i_ = 0; i_ < 16; ++i_) { S0_[i_] = 0.f; S1_[i_] = 0.f; } \
;     _Pragma("unroll") for (int kk_ = 0; kk_ < 4; ++kk_) { \
;       S0_ = __builtin_amdgcn_mfma_f32_32x32x16_bf16(kf_[kk_], qf[0][kk_], S0_, 0, 0, 0); \
;       S1_ = __builtin_amdgcn_mfma_f32_32x32x16_bf16(kf_[kk_], qf[1][kk_], S1_, 0, 0, 0); } } while (0)
; #define ATT_PV(vf_, P0_, P1_) do { \
;     _Pragma("unroll") for (int c_ = 0; c_ < 2; ++c_) \
;     _Pragma("unroll") for (int db_ = 0; db_ < 2; ++db_) { \
;       O[db_][0] = __builtin_amdgcn_mfma_f32_32x32x16_bf16(vf_[db_ * 2 + c_], P0_[c_], O[db_][0], 0, 0, 0); \
;       O[db_][1] = __builtin_amdgcn_mfma_f32_32x32x16_bf16(vf_[db_ * 2 + c_], P1_[c_], O[db_][1], 0, 0, 0); } } while (0)
; #define WBAR() do { __builtin_amdgcn_sched_barrier(0); __builtin_amdgcn_s_barrier(); __builtin_amdgcn_sched_barrier(0); } while (0)
; __device__ __forceinline__ void attn_item_fast(const u16* __restrict__ Qg, const u16* __restrict__ Kg, const u16* __restrict__ Vtg,
;                                                u16* __restrict__ Og, const int L, char* smem, const int tid) {
;     ...
;     exp_pack(S0, l0, P0[0], P0[1]); exp_pack(S1, l1, P1[0], P1[1]);
;     WBAR();
;     ATT_PV(vf, P0, P1);
;     ld_vf<1>(vf, Vb, r32, hi, sw);
;     ATT_QK(S0, S1, kf);
;     asm volatile("s_waitcnt vmcnt(0) lgkmcnt(0)" ::: "memory");
;     WBAR();
;     exp_pack(S0, l0, P0[0], P0[1]); exp_pack(S1, l1, P1[0], P1[1]);
;     WBAR();
	s_setprio 0
	s_nop 10
	v_exp_f32_e32 v82, v82
	v_exp_f32_e32 v148, v83
	v_exp_f32_e32 v84, v84
	v_exp_f32_e32 v150, v85
	v_exp_f32_e32 v83, v66
	v_exp_f32_e32 v149, v67
	v_exp_f32_e32 v85, v68
	v_exp_f32_e32 v151, v69
	v_exp_f32_e32 v86, v86
	v_exp_f32_e32 v152, v87
	v_exp_f32_e32 v88, v88
	v_exp_f32_e32 v154, v89
	v_exp_f32_e32 v87, v70
	v_exp_f32_e32 v153, v71
	v_exp_f32_e32 v89, v72
	v_exp_f32_e32 v155, v73
	v_exp_f32_e32 v90, v90
	v_exp_f32_e32 v156, v91
	v_exp_f32_e32 v92, v92
	v_exp_f32_e32 v158, v93
	v_exp_f32_e32 v91, v74
	v_exp_f32_e32 v157, v75
	v_exp_f32_e32 v93, v76
	v_exp_f32_e32 v159, v77
	v_exp_f32_e32 v94, v94
	v_exp_f32_e32 v160, v95
	v_exp_f32_e32 v96, v96
	v_exp_f32_e32 v178, v97
	v_exp_f32_e32 v95, v78
	v_exp_f32_e32 v161, v79
	v_exp_f32_e32 v97, v80
	v_exp_f32_e32 v179, v81
	v_add_f32_e32 v66, v82, v148
	v_add_f32_e32 v67, v83, v149
	v_add_f32_e32 v68, v84, v150
	v_add_f32_e32 v69, v85, v151
	v_add_f32_e32 v70, v88, v154
	v_add_f32_e32 v71, v89, v155
	v_add_f32_e32 v66, v66, v68
	v_add_f32_e32 v67, v67, v69
	v_add_f32_e32 v68, v86, v152
	v_add_f32_e32 v69, v87, v153
	v_add_f32_e32 v72, v92, v158
	v_add_f32_e32 v73, v93, v159
	v_add_f32_e32 v68, v68, v70
	v_add_f32_e32 v69, v69, v71
	v_add_f32_e32 v70, v90, v156
	v_add_f32_e32 v71, v91, v157
	v_add_f32_e32 v74, v96, v178
	v_add_f32_e32 v75, v97, v179
	v_add_f32_e32 v70, v70, v72
	v_add_f32_e32 v71, v71, v73
	v_add_f32_e32 v72, v94, v160
	v_add_f32_e32 v73, v95, v161
	v_add_f32_e32 v66, v66, v68
	v_add_f32_e32 v67, v67, v69
	v_add_f32_e32 v72, v72, v74
	v_add_f32_e32 v73, v73, v75
	v_cvt_pk_bf16_f32 v74, v82, v148
	v_cvt_pk_bf16_f32 v75, v84, v150
	v_cvt_pk_bf16_f32 v76, v86, v152
	v_cvt_pk_bf16_f32 v77, v88, v154
	v_cvt_pk_bf16_f32 v78, v83, v149
	s_nop 0
	v_add_f32_e32 v68, v70, v72
	v_add_f32_e32 v69, v71, v73
	v_cvt_pk_bf16_f32 v70, v90, v156
	v_cvt_pk_bf16_f32 v71, v92, v158
	v_cvt_pk_bf16_f32 v72, v94, v160
	v_cvt_pk_bf16_f32 v73, v96, v178
	v_cvt_pk_bf16_f32 v79, v85, v151
	s_nop 0
	v_add_f32_e32 v66, v66, v68
	v_add_f32_e32 v67, v67, v69
	v_cvt_pk_bf16_f32 v80, v87, v153
	v_cvt_pk_bf16_f32 v81, v89, v155
	v_cvt_pk_bf16_f32 v68, v95, v161
	v_cvt_pk_bf16_f32 v69, v97, v179
	s_nop 0
	v_add_f32_e32 v162, v146, v66
	v_add_f32_e32 v163, v147, v67
	v_cvt_pk_bf16_f32 v66, v91, v157
	v_cvt_pk_bf16_f32 v67, v93, v159
	s_barrier
	s_setprio 1
	s_addk_i32 s53, 0x2000
	s_add_u32 s10, s10, 0x8000
	s_addc_u32 s11, s11, 0
	s_add_u32 s34, s34, 0x80
	s_addc_u32 s35, s35, 0
	s_cmp_eq_u32 s53, 0x3e000
	s_cbranch_scc0 .LBB0_102
	v_add_u32_e32 v175, v170, v171
	ds_read_b128 v[146:149], v175 offset:8192
	s_waitcnt lgkmcnt(4)
	v_mfma_f32_32x32x16_bf16 v[50:65], v[142:145], v[74:77], v[50:65]
	v_add_u32_e32 v176, v170, v172
	ds_read_b128 v[150:153], v176 offset:8192
	v_add_u32_e32 v205, v170, v173
	ds_read_b128 v[154:157], v205 offset:8192
	v_add_u32_e32 v226, v170, v174
	ds_read_b128 v[158:161], v226 offset:8192
	ds_read_b128 v[178:181], v175 offset:24576
	ds_read_b128 v[182:185], v176 offset:24576
	ds_read_b128 v[186:189], v175 offset:28672
	ds_read_b128 v[206:209], v176 offset:28672
	v_mfma_f32_32x32x16_bf16 v[18:33], v[142:145], v[78:81], v[18:33]
	ds_read_b128 v[210:213], v175 offset:12288
	ds_read_b128 v[214:217], v176 offset:12288
	ds_read_b128 v[218:221], v205 offset:12288
	ds_read_b128 v[222:225], v226 offset:12288
	s_waitcnt lgkmcnt(14)
	v_mfma_f32_32x32x16_bf16 v[34:49], v[138:141], v[74:77], v[34:49]
	v_mfma_f32_32x32x16_bf16 v[2:17], v[138:141], v[78:81], v[2:17]
	s_waitcnt lgkmcnt(13)
	v_mfma_f32_32x32x16_bf16 v[50:65], v[134:137], v[70:73], v[50:65]
	v_mfma_f32_32x32x16_bf16 v[18:33], v[134:137], v[66:69], v[18:33]
	s_waitcnt lgkmcnt(12)
	v_mfma_f32_32x32x16_bf16 v[34:49], v[130:133], v[70:73], v[34:49]
	v_mfma_f32_32x32x16_bf16 v[2:17], v[130:133], v[66:69], v[2:17]
	s_waitcnt lgkmcnt(11)
	v_mfma_f32_32x32x16_bf16 v[82:97], v[146:149], v[118:121], 0
	v_mfma_f32_32x32x16_bf16 v[66:81], v[146:149], v[126:129], 0
	s_waitcnt lgkmcnt(10)
	v_mfma_f32_32x32x16_bf16 v[82:97], v[150:153], v[114:117], v[82:97]
	v_mfma_f32_32x32x16_bf16 v[66:81], v[150:153], v[122:125], v[66:81]
	s_waitcnt lgkmcnt(9)
	v_mfma_f32_32x32x16_bf16 v[82:97], v[154:157], v[106:109], v[82:97]
	v_mfma_f32_32x32x16_bf16 v[66:81], v[154:157], v[110:113], v[66:81]
	s_waitcnt lgkmcnt(8)
	v_mfma_f32_32x32x16_bf16 v[82:97], v[158:161], v[102:105], v[82:97]
	v_mfma_f32_32x32x16_bf16 v[66:81], v[158:161], v[98:101], v[66:81]
	s_barrier
; #define ATT_QK(S0_, S1_, kf_) do { \
;     _Pragma("unroll") for (int i_ = 0; i_ < 16; ++i_) { S0_[i_] = 0.f; S1_[i_] = 0.f; } \
;     _Pragma("unroll") for (int kk_ = 0; kk_ < 4; ++kk_) { \
;       S0_ = __builtin_amdgcn_mfma_f32_32x32x16_bf16(kf_[kk_], qf[0][kk_], S0_, 0, 0, 0); \
;       S1_ = __builtin_amdgcn_mfma_f32_32x32x16_bf16(kf_[kk_], qf[1][kk_], S1_, 0, 0, 0); } } while (0)
; #define ATT_PV(vf_, P0_, P1_) do { \
;     _Pragma("unroll") for (int c_ = 0; c_ < 2; ++c_) \
;     _Pragma("unroll") for (int db_ = 0; db_ < 2; ++db_) { \
;       O[db_][0] = __builtin_amdgcn_mfma_f32_32x32x16_bf16(vf_[db_ * 2 + c_], P0_[c_], O[db_][0], 0, 0, 0); \
;       O[db_][1] = __builtin_amdgcn_mfma_f32_32x32x16_bf16(vf_[db_ * 2 + c_], P1_[c_], O[db_][1], 0, 0, 0); } } while (0)
; #define WBAR() do { __builtin_amdgcn_sched_barrier(0); __builtin_amdgcn_s_barrier(); __builtin_amdgcn_sched_barrier(0); } while (0)
; __device__ __forceinline__ void attn_item_fast(const u16* __restrict__ Qg, const u16* __restrict__ Kg, const u16* __restrict__ Vtg,
;                                                u16* __restrict__ Og, const int L, char* smem, const int tid) {
;     ...
;     ld_kf<0>(kf, Kb, r32, hi, sw);
;     ATT_PV(vf, P0, P1);
;     ld_vf<0>(vf, Vb, r32, hi, sw);
;     ATT_QK(S0, S1, kf);
;     ld_kf<1>(kf, Kb, r32, hi, sw);
;     WBAR();
;     exp_pack(S0, l0, P0[0], P0[1]); exp_pack(S1, l1, P1[0], P1[1]);
;     WBAR();
;     ATT_PV(vf, P0, P1);
;     ld_vf<1>(vf, Vb, r32, hi, sw);
;     ATT_QK(S0, S1, kf);
;     asm volatile("s_waitcnt vmcnt(0) lgkmcnt(0)" ::: "memory");
;     WBAR();
;     exp_pack(S0, l0, P0[0], P0[1]); exp_pack(S1, l1, P1[0], P1[1]);
;     WBAR();
;   }
;   if (half == 0) WBAR();
	s_nop 9
	v_exp_f32_e32 v138, v82
	v_exp_f32_e32 v144, v83
	v_exp_f32_e32 v132, v84
	v_exp_f32_e32 v139, v85
	v_exp_f32_e32 v133, v86
	v_exp_f32_e32 v140, v87
	v_exp_f32_e32 v141, v88
	v_exp_f32_e32 v145, v89
	v_exp_f32_e32 v134, v90
	v_exp_f32_e32 v142, v91
	v_exp_f32_e32 v130, v92
	v_exp_f32_e32 v135, v93
	v_exp_f32_e32 v131, v94
	v_exp_f32_e32 v136, v95
	v_exp_f32_e32 v137, v96
	v_exp_f32_e32 v143, v97
	v_exp_f32_e32 v146, v66
	v_exp_f32_e32 v147, v67
	v_exp_f32_e32 v148, v68
	v_exp_f32_e32 v151, v69
	v_exp_f32_e32 v149, v70
	v_exp_f32_e32 v152, v71
	v_exp_f32_e32 v153, v72
	v_exp_f32_e32 v157, v73
	v_exp_f32_e32 v150, v74
	v_exp_f32_e32 v154, v75
	v_exp_f32_e32 v155, v76
	v_exp_f32_e32 v158, v77
	v_exp_f32_e32 v156, v78
	v_exp_f32_e32 v159, v79
	v_exp_f32_e32 v160, v80
	v_exp_f32_e32 v161, v81
	v_cvt_pk_bf16_f32 v82, v138, v144
	v_cvt_pk_bf16_f32 v83, v132, v139
	v_cvt_pk_bf16_f32 v84, v133, v140
	v_cvt_pk_bf16_f32 v85, v141, v145
	v_cvt_pk_bf16_f32 v86, v134, v142
	v_cvt_pk_bf16_f32 v87, v130, v135
	v_cvt_pk_bf16_f32 v88, v131, v136
	v_cvt_pk_bf16_f32 v89, v137, v143
	v_cvt_pk_bf16_f32 v66, v146, v147
	v_cvt_pk_bf16_f32 v67, v148, v151
	v_cvt_pk_bf16_f32 v68, v149, v152
	v_cvt_pk_bf16_f32 v69, v153, v157
	v_cvt_pk_bf16_f32 v70, v150, v154
	v_cvt_pk_bf16_f32 v71, v155, v158
	v_cvt_pk_bf16_f32 v72, v156, v159
	v_cvt_pk_bf16_f32 v73, v160, v161
	s_barrier
	s_waitcnt lgkmcnt(7)
	v_mfma_f32_32x32x16_bf16 v[50:65], v[178:181], v[82:85], v[50:65]
	v_mfma_f32_32x32x16_bf16 v[18:33], v[178:181], v[66:69], v[18:33]
	s_waitcnt lgkmcnt(5)
	v_mfma_f32_32x32x16_bf16 v[34:49], v[186:189], v[82:85], v[34:49]
	v_mfma_f32_32x32x16_bf16 v[2:17], v[186:189], v[66:69], v[2:17]
	v_mfma_f32_32x32x16_bf16 v[50:65], v[182:185], v[86:89], v[50:65]
	v_mfma_f32_32x32x16_bf16 v[18:33], v[182:185], v[70:73], v[18:33]
	s_waitcnt lgkmcnt(4)
	v_mfma_f32_32x32x16_bf16 v[34:49], v[206:209], v[86:89], v[34:49]
	v_mfma_f32_32x32x16_bf16 v[2:17], v[206:209], v[70:73], v[2:17]
	s_waitcnt lgkmcnt(3)
	v_mfma_f32_32x32x16_bf16 v[82:97], v[210:213], v[118:121], 0
	v_mfma_f32_32x32x16_bf16 v[66:81], v[210:213], v[126:129], 0
	s_waitcnt lgkmcnt(2)
	v_mfma_f32_32x32x16_bf16 v[82:97], v[214:217], v[114:117], v[82:97]
	v_mfma_f32_32x32x16_bf16 v[66:81], v[214:217], v[122:125], v[66:81]
	s_waitcnt lgkmcnt(1)
	v_mfma_f32_32x32x16_bf16 v[82:97], v[218:221], v[106:109], v[82:97]
	v_mfma_f32_32x32x16_bf16 v[66:81], v[218:221], v[110:113], v[66:81]
	s_waitcnt lgkmcnt(0)
	v_mfma_f32_32x32x16_bf16 v[82:97], v[222:225], v[102:105], v[82:97]
	ds_read_b128 v[114:117], v205 offset:24576
	ds_read_b128 v[110:113], v205 offset:28672
	ds_read_b128 v[106:109], v226 offset:24576
	ds_read_b128 v[102:105], v226 offset:28672
	s_waitcnt vmcnt(0) lgkmcnt(0)
	v_mfma_f32_32x32x16_bf16 v[66:81], v[222:225], v[98:101], v[66:81]
	s_barrier
	s_nop 5
	v_exp_f32_e32 v98, v82
	v_exp_f32_e32 v99, v83
	v_exp_f32_e32 v100, v84
	v_exp_f32_e32 v119, v85
	v_exp_f32_e32 v101, v86
	v_exp_f32_e32 v120, v87
	v_exp_f32_e32 v121, v88
	v_exp_f32_e32 v122, v89
	v_exp_f32_e32 v90, v90
	v_exp_f32_e32 v91, v91
	v_exp_f32_e32 v92, v92
	v_exp_f32_e32 v118, v93
	v_exp_f32_e32 v93, v94
	v_exp_f32_e32 v94, v95
	v_exp_f32_e32 v95, v96
	v_exp_f32_e32 v96, v97
	v_exp_f32_e32 v175, v66
	v_exp_f32_e32 v176, v67
	v_exp_f32_e32 v178, v68
	v_exp_f32_e32 v179, v69
	v_exp_f32_e32 v97, v70
	v_exp_f32_e32 v124, v71
	v_exp_f32_e32 v125, v72
	v_exp_f32_e32 v128, v73
	v_exp_f32_e32 v123, v74
	v_exp_f32_e32 v126, v75
	v_exp_f32_e32 v127, v76
	v_exp_f32_e32 v129, v77
	v_exp_f32_e32 v74, v78
	v_exp_f32_e32 v75, v79
	v_exp_f32_e32 v76, v80
	v_exp_f32_e32 v77, v81
	v_cvt_pk_bf16_f32 v86, v98, v99
	v_cvt_pk_bf16_f32 v87, v100, v119
	v_cvt_pk_bf16_f32 v88, v101, v120
	v_cvt_pk_bf16_f32 v89, v121, v122
	v_cvt_pk_bf16_f32 v82, v90, v91
	v_cvt_pk_bf16_f32 v83, v92, v118
	v_cvt_pk_bf16_f32 v84, v93, v94
	v_cvt_pk_bf16_f32 v85, v95, v96
	v_cvt_pk_bf16_f32 v70, v175, v176
	v_cvt_pk_bf16_f32 v71, v178, v179
	v_cvt_pk_bf16_f32 v72, v97, v124
	v_cvt_pk_bf16_f32 v73, v125, v128
	v_cvt_pk_bf16_f32 v66, v123, v126
	v_cvt_pk_bf16_f32 v67, v127, v129
	v_cvt_pk_bf16_f32 v68, v74, v75
	v_cvt_pk_bf16_f32 v69, v76, v77
	s_barrier
	s_cmpk_lt_u32 s14, 0x100
	s_cbranch_scc0 .LBB0_98
	s_barrier
	s_branch .LBB0_98
